# lever 2: LRU phase set-up de-serialised: gate-weight loads stay in flight across the parameter set-up, their LDS writes are issued at the end of the set-up
# speedup vs baseline: 1.0092x; 1.0092x over previous
; #define LAS __attribute__((address_space(3)))
; template <int PASS>
; __device__ __forceinline__ void lru_phase(Frame& F, const Params& p) {
;     ...
;     for (int i = F.tid; i < 4 * 64 * 8; i += NTHREADS) {
;         const int c = i & 7, j = (i >> 3) & 63, m = i >> 9, d = m >> 1, gt = m & 1;
;         const u32x4 w = *(const u32x4*)((const bf16*)(F.ws + WS_LW) + ((size_t)(((d * 16 + head) * 2 + gt) * 64 + j) * 64 + 8 * c));
;         *(LAS u32x4*)(lw + (m * 64 + j) * LRU_WROW + 8 * c) = w;
;     }
.LBB0_662:
	v_mov_b32_e32 v17, 0
	v_add_u32_e32 v24, 0, v4
	v_add_u32_e32 v25, 0, v1
	v_lshrrev_b32_e32 v16, 6, v24
	v_lshlrev_b32_e32 v20, 1, v25
	v_and_b32_e32 v21, 0x1fffff0, v16
	v_ashrrev_i32_e32 v23, 3, v24
	v_and_b32_e32 v16, 0x70, v20
	v_or_b32_e32 v20, s48, v21
	v_bfe_u32 v18, v24, 3, 6
	v_and_b32_e32 v22, 64, v23
	v_lshlrev_b32_e32 v20, 7, v20
	v_or3_b32 v20, v20, v22, v18
	v_ashrrev_i32_e32 v21, 31, v20
	v_lshlrev_b64 v[20:21], 7, v[20:21]
	v_lshl_add_u64 v[20:21], s[6:7], 0, v[20:21]
	v_lshl_add_u64 v[20:21], v[20:21], 0, v[16:17]
	global_load_dwordx4 v[40:43], v[20:21], off
	v_and_or_b32 v18, v23, s10, v18
	v_mul_lo_u32 v18, v18, s11
	v_add3_u32 v36, 0, v18, v16
	v_add_u32_e32 v24, 512, v4
	v_add_u32_e32 v25, 4096, v1
	v_lshrrev_b32_e32 v16, 6, v24
	v_lshlrev_b32_e32 v20, 1, v25
	v_and_b32_e32 v21, 0x1fffff0, v16
	v_ashrrev_i32_e32 v23, 3, v24
	v_and_b32_e32 v16, 0x70, v20
	v_or_b32_e32 v20, s48, v21
	v_bfe_u32 v18, v24, 3, 6
	v_and_b32_e32 v22, 64, v23
	v_lshlrev_b32_e32 v20, 7, v20
	v_or3_b32 v20, v20, v22, v18
	v_ashrrev_i32_e32 v21, 31, v20
	v_lshlrev_b64 v[20:21], 7, v[20:21]
	v_lshl_add_u64 v[20:21], s[6:7], 0, v[20:21]
	v_lshl_add_u64 v[20:21], v[20:21], 0, v[16:17]
	global_load_dwordx4 v[44:47], v[20:21], off
	v_and_or_b32 v18, v23, s10, v18
	v_mul_lo_u32 v18, v18, s11
	v_add3_u32 v37, 0, v18, v16
	v_add_u32_e32 v24, 1024, v4
	v_add_u32_e32 v25, 8192, v1
	v_lshrrev_b32_e32 v16, 6, v24
	v_lshlrev_b32_e32 v20, 1, v25
	v_and_b32_e32 v21, 0x1fffff0, v16
	v_ashrrev_i32_e32 v23, 3, v24
	v_and_b32_e32 v16, 0x70, v20
	v_or_b32_e32 v20, s48, v21
	v_bfe_u32 v18, v24, 3, 6
	v_and_b32_e32 v22, 64, v23
	v_lshlrev_b32_e32 v20, 7, v20
	v_or3_b32 v20, v20, v22, v18
	v_ashrrev_i32_e32 v21, 31, v20
	v_lshlrev_b64 v[20:21], 7, v[20:21]
	v_lshl_add_u64 v[20:21], s[6:7], 0, v[20:21]
	v_lshl_add_u64 v[20:21], v[20:21], 0, v[16:17]
	global_load_dwordx4 v[48:51], v[20:21], off
	v_and_or_b32 v18, v23, s10, v18
	v_mul_lo_u32 v18, v18, s11
	v_add3_u32 v38, 0, v18, v16
	v_add_u32_e32 v24, 1536, v4
	v_add_u32_e32 v25, 12288, v1
	v_lshrrev_b32_e32 v16, 6, v24
	v_lshlrev_b32_e32 v20, 1, v25
	v_and_b32_e32 v21, 0x1fffff0, v16
	v_ashrrev_i32_e32 v23, 3, v24
	v_and_b32_e32 v16, 0x70, v20
	v_or_b32_e32 v20, s48, v21
	v_bfe_u32 v18, v24, 3, 6
	v_and_b32_e32 v22, 64, v23
	v_lshlrev_b32_e32 v20, 7, v20
	v_or3_b32 v20, v20, v22, v18
	v_ashrrev_i32_e32 v21, 31, v20
	v_lshlrev_b64 v[20:21], 7, v[20:21]
	v_lshl_add_u64 v[20:21], s[6:7], 0, v[20:21]
	v_lshl_add_u64 v[20:21], v[20:21], 0, v[16:17]
	global_load_dwordx4 v[52:55], v[20:21], off
	v_and_or_b32 v18, v23, s10, v18
	v_mul_lo_u32 v18, v18, s11
	v_add3_u32 v39, 0, v18, v16

; #define LAS __attribute__((address_space(3)))
; template <int PASS>
; __device__ __forceinline__ void lru_phase(Frame& F, const Params& p) {
;     ...
;     for (int i = F.tid; i < 4 * 64 * 8; i += NTHREADS) {
;         const int c = i & 7, j = (i >> 3) & 63, m = i >> 9, d = m >> 1, gt = m & 1;
;         const u32x4 w = *(const u32x4*)((const bf16*)(F.ws + WS_LW) + ((size_t)(((d * 16 + head) * 2 + gt) * 64 + j) * 64 + 8 * c));
;         *(LAS u32x4*)(lw + (m * 64 + j) * LRU_WROW + 8 * c) = w;
;     }
;     for (int i = F.tid; i < 2 * 64; i += NTHREADS) {
;         const int d = i >> 6, c = i & 63, ch = head * 64 + c; const float lam = p.in[19][d * LRUW + ch];
;         prm[(d * 3 + 0) * 64 + c] = -1.4426950408889634f * p.in[21][d * LRUW + ch]; prm[(d * 3 + 1) * 64 + c] = -1.4426950408889634f * p.in[23][d * LRUW + ch];
;         prm[(d * 3 + 2) * 64 + c] = 1.4426950408889634f * -8.f * (lam > 15.f ? __expf(-lam) : log1pf(__expf(-lam)));
;     }
;     for (int i = F.tid; i < 5 * 64; i += NTHREADS) { const int k = i >> 6, c = i & 63; cwl[i] = (k < 4) ? p.in[17][k * LRUW + head * 64 + c] : p.in[18][head * 64 + c]; }
;     __syncthreads();
;     const int wg = (F.bx >> 4) * NWAVES + F.wave, NWG = (F.G >> 4) * NWAVES;
;     const int nitems = 2 * 65 * 8;
;     {
;         LAS unsigned char* pf = F.lds + 40960 + NWAVES * (32 * 68 * 4) + F.wave * 4480;
;         int it = wg;
;         if (PASS == 2) while (it < nitems && ((it >> 3) % 65) == 64) it += NWG;
;         if (it < nitems) { int ln = F.lane; asm volatile("" : "+v"(ln)); lru_prefetch(F.ws, pf, ln, head, it); }
.LBB0_681:
	s_or_b64 exec, exec, s[28:29]
	s_waitcnt vmcnt(0)
	ds_write_b128 v36, v[40:43]
	ds_write_b128 v37, v[44:47]
	ds_write_b128 v38, v[48:51]
	ds_write_b128 v39, v[52:55]
	s_mul_i32 s4, s95, 0x2200
	s_add_i32 s44, s4, 0
	s_ashr_i32 s4, s2, 1
	s_and_b32 s4, s4, -8
	s_add_i32 s47, s95, s4
	s_ashr_i32 s4, s58, 1
	s_and_b32 s45, s4, -8
	s_mul_i32 s4, s95, 0x1180
	s_add_i32 s46, s4, 0
	s_add_i32 s46, s46, 0x1b000
	s_cmpk_lt_i32 s47, 0x410
	s_cselect_b64 s[28:29], -1, 0
	s_and_b64 vcc, exec, s[28:29]
	s_waitcnt lgkmcnt(0)
	s_barrier
	s_cbranch_vccz .LBB0_714
	s_ashr_i32 s4, s47, 3
	s_mul_hi_i32 s5, s4, 0x7e07e07f
	s_lshr_b32 s6, s5, 31
	s_ashr_i32 s5, s5, 5
	s_add_i32 s6, s5, s6
	s_mul_i32 s5, s6, 0x41
	s_sub_i32 s7, s4, s5
	s_cmp_lt_i32 s7, 64
	s_cselect_b64 s[4:5], -1, 0
	s_lshl_b32 s8, s6, 8
	s_lshl_b32 s6, s6, 14
	s_add_i32 s9, s6, s7
	s_and_b64 s[6:7], s[4:5], exec
	s_mov_b32 s7, 0x1e000000
	s_cselect_b32 s7, s7, 0x3e300000
	s_cselect_b32 s6, s9, s8
	s_add_u32 s8, s56, s7
	s_addc_u32 s9, s57, 0
	s_ashr_i32 s7, s6, 31
	s_lshl_b64 s[6:7], s[6:7], 11
	s_add_u32 s6, s8, s6
	s_addc_u32 s7, s9, s7
	s_lshl_b32 s16, s48, 7
	s_add_u32 s6, s6, s16
	v_mov_b32_e32 v0, v108
	s_addc_u32 s7, s7, 0
	s_and_b32 s10, s55, 0xe0
	s_movk_i32 s8, 0x118
	s_add_i32 s10, s10, -1
	v_cmp_gt_i32_e32 vcc, s8, v0
	v_lshrrev_b32_e32 v1, 4, v0
	s_and_saveexec_b64 s[8:9], vcc
	s_cbranch_execz .LBB0_684
	v_ashrrev_i32_e32 v2, 3, v0
	v_add_u32_e32 v2, s10, v2
	v_mov_b32_e32 v3, 0xff
	s_and_b64 s[12:13], s[4:5], exec
	v_med3_i32 v2, v2, 0, v3
	v_xor_b32_e32 v6, v1, v0
	v_mov_b32_e32 v3, 0
	s_cselect_b32 s11, 16, 10
	v_lshlrev_b64 v[4:5], s11, v[2:3]
	v_lshlrev_b32_e32 v2, 4, v6
	v_lshl_add_u64 v[4:5], v[4:5], 1, s[6:7]
	v_and_b32_e32 v2, 0x70, v2
	v_lshl_add_u64 v[2:3], v[4:5], 0, v[2:3]
	s_mov_b32 m0, s46
	s_nop 0
	global_load_lds_dwordx4 v[2:3], off

; #define LAS __attribute__((address_space(3)))
; template <int PASS>
; __device__ __forceinline__ void lru_phase(Frame& F, const Params& p) {
;     ...
;     for (int i = F.tid; i < 4 * 64 * 8; i += NTHREADS) {
;         const int c = i & 7, j = (i >> 3) & 63, m = i >> 9, d = m >> 1, gt = m & 1;
;         const u32x4 w = *(const u32x4*)((const bf16*)(F.ws + WS_LW) + ((size_t)(((d * 16 + head) * 2 + gt) * 64 + j) * 64 + 8 * c));
;         *(LAS u32x4*)(lw + (m * 64 + j) * LRU_WROW + 8 * c) = w;
;     }
;     for (int i = F.tid; i < 2 * 64; i += NTHREADS) {
;         const int d = i >> 6, c = i & 63, ch = head * 64 + c; const float lam = p.in[19][d * LRUW + ch];
;         prm[(d * 3 + 0) * 64 + c] = -1.4426950408889634f * p.in[21][d * LRUW + ch]; prm[(d * 3 + 1) * 64 + c] = -1.4426950408889634f * p.in[23][d * LRUW + ch];
;         prm[(d * 3 + 2) * 64 + c] = 1.4426950408889634f * -8.f * (lam > 15.f ? __expf(-lam) : log1pf(__expf(-lam)));
;     }
;     for (int i = F.tid; i < 5 * 64; i += NTHREADS) { const int k = i >> 6, c = i & 63; cwl[i] = (k < 4) ? p.in[17][k * LRUW + head * 64 + c] : p.in[18][head * 64 + c]; }
;     __syncthreads();
.LBB0_881:
	s_or_b64 exec, exec, s[34:35]
	s_waitcnt vmcnt(0)
	ds_write_b128 v36, v[40:43]
	ds_write_b128 v37, v[44:47]
	ds_write_b128 v38, v[48:51]
	ds_write_b128 v39, v[52:55]
	s_andn2_b64 vcc, exec, s[28:29]
	s_waitcnt lgkmcnt(0)
	s_barrier
	s_cbranch_vccnz .LBB0_899
